# prepass S5 coefficient tables: the per-state input loads are issued up front (eight wide loads / 32 dword loads) instead of a load-wait-compute-store chain per step
# speedup vs baseline: 1.0058x; 1.0058x over previous
; __device__ __forceinline__ bf16_t f2bf(float f) { return (bf16_t)(cvt_pk_bf16(f, 0.f) & 0xffffu); }
; __device__ __forceinline__ float bf2f(bf16_t b) { return __uint_as_float(((unsigned)b) << 16); }
; __device__ __forceinline__ void phase_prepass(ParamsK p, LAS unsigned char* lds) {
;     ...
;         const float* br = p->in[11] + (size_t)i * 16; const float* bi = p->in[12] + (size_t)i * 16;
;         f32x2* bo = (f32x2*)(p->ws + WS_S5B) + (size_t)i * 16;
;         bf16_t* bmt = (bf16_t*)(p->ws + WS_S5BM) + (size_t)(l * 64 + g) * 2 * 128 * 16;
; #pragma unroll 1
;         for (int n = 0; n < 16; ++n) { const double b_r = br[n], b_i = bi[n]; const float vr = (float)(fr * b_r - fi * b_i), vi = (float)(fr * b_i + fi * b_r);
;             bo[n] = (f32x2){vr, vi}; const bf16_t hr = f2bf(vr), hi = f2bf(vi);
;             bmt[pp * 16 + n] = hr; bmt[(64 + pp) * 16 + n] = hi; bmt[2048 + pp * 16 + n] = f2bf(vr - bf2f(hr)); bmt[2048 + (64 + pp) * 16 + n] = f2bf(vi - bf2f(hi)); }
.LBB0_135:
	global_load_dwordx4 v[100:103], v[68:69], off
	global_load_dwordx4 v[104:107], v[68:69], off offset:16
	global_load_dwordx4 v[108:111], v[68:69], off offset:32
	global_load_dwordx4 v[112:115], v[68:69], off offset:48
	global_load_dwordx4 v[116:119], v[70:71], off
	global_load_dwordx4 v[120:123], v[70:71], off offset:16
	global_load_dwordx4 v[124:127], v[70:71], off offset:32
	global_load_dwordx4 v[128:131], v[70:71], off offset:48
	s_waitcnt vmcnt(0)
	v_lshl_add_u64 v[76:77], s[4:5], 0, v[66:67]
	v_add_co_u32_e32 v78, vcc, s56, v76
	v_lshl_add_u64 v[74:75], s[4:5], 0, v[72:73]
	s_nop 0
	v_addc_co_u32_e32 v79, vcc, 0, v77, vcc
	v_add_co_u32_e32 v76, vcc, s57, v76
	v_lshl_add_u64 v[66:67], v[66:67], 0, 2
	v_lshl_add_u64 v[72:73], v[72:73], 0, 8
	v_addc_co_u32_e32 v77, vcc, 0, v77, vcc
	v_cvt_f64_f32_e32 v[82:83], v100
	v_cvt_f64_f32_e32 v[80:81], v116
	v_mul_f64 v[84:85], v[64:65], v[82:83]
	v_mul_f64 v[82:83], v[62:63], v[82:83]
	v_fma_f64 v[84:85], v[62:63], v[80:81], -v[84:85]
	v_fmac_f64_e32 v[82:83], v[64:65], v[80:81]
	v_cvt_f32_f64_e32 v80, v[84:85]
	v_cvt_f32_f64_e32 v81, v[82:83]
	v_cvt_pk_bf16_f32 v3, v80, s0
	global_store_dwordx2 v[74:75], v[80:81], off
	v_cvt_pk_bf16_f32 v7, v81, s0
	global_store_short v[78:79], v3, off offset:1024
	global_store_short v[78:79], v7, off offset:3072
	v_lshlrev_b32_e32 v3, 16, v3
	v_lshlrev_b32_e32 v7, 16, v7
	v_sub_f32_e32 v3, v80, v3
	v_sub_f32_e32 v7, v81, v7
	v_cvt_pk_bf16_f32 v3, v3, s0
	v_cvt_pk_bf16_f32 v7, v7, s0
	global_store_short v[76:77], v3, off offset:1024
	global_store_short v[76:77], v7, off offset:3072
	v_lshl_add_u64 v[76:77], s[4:5], 0, v[66:67]
	v_add_co_u32_e32 v78, vcc, s56, v76
	v_lshl_add_u64 v[74:75], s[4:5], 0, v[72:73]
	s_nop 0
	v_addc_co_u32_e32 v79, vcc, 0, v77, vcc
	v_add_co_u32_e32 v76, vcc, s57, v76
	v_lshl_add_u64 v[66:67], v[66:67], 0, 2
	v_lshl_add_u64 v[72:73], v[72:73], 0, 8
	v_addc_co_u32_e32 v77, vcc, 0, v77, vcc
	v_cvt_f64_f32_e32 v[82:83], v101
	v_cvt_f64_f32_e32 v[80:81], v117
	v_mul_f64 v[84:85], v[64:65], v[82:83]
	v_mul_f64 v[82:83], v[62:63], v[82:83]
	v_fma_f64 v[84:85], v[62:63], v[80:81], -v[84:85]
	v_fmac_f64_e32 v[82:83], v[64:65], v[80:81]
	v_cvt_f32_f64_e32 v80, v[84:85]
	v_cvt_f32_f64_e32 v81, v[82:83]
	v_cvt_pk_bf16_f32 v3, v80, s0
	global_store_dwordx2 v[74:75], v[80:81], off
	v_cvt_pk_bf16_f32 v7, v81, s0
	global_store_short v[78:79], v3, off offset:1024
	global_store_short v[78:79], v7, off offset:3072
	v_lshlrev_b32_e32 v3, 16, v3
	v_lshlrev_b32_e32 v7, 16, v7
	v_sub_f32_e32 v3, v80, v3
	v_sub_f32_e32 v7, v81, v7
	v_cvt_pk_bf16_f32 v3, v3, s0
	v_cvt_pk_bf16_f32 v7, v7, s0
	global_store_short v[76:77], v3, off offset:1024
	global_store_short v[76:77], v7, off offset:3072
	v_lshl_add_u64 v[76:77], s[4:5], 0, v[66:67]
	v_add_co_u32_e32 v78, vcc, s56, v76
	v_lshl_add_u64 v[74:75], s[4:5], 0, v[72:73]
	s_nop 0
	v_addc_co_u32_e32 v79, vcc, 0, v77, vcc
	v_add_co_u32_e32 v76, vcc, s57, v76
	v_lshl_add_u64 v[66:67], v[66:67], 0, 2
	v_lshl_add_u64 v[72:73], v[72:73], 0, 8
	v_addc_co_u32_e32 v77, vcc, 0, v77, vcc
	v_cvt_f64_f32_e32 v[82:83], v102
	v_cvt_f64_f32_e32 v[80:81], v118
	v_mul_f64 v[84:85], v[64:65], v[82:83]
	v_mul_f64 v[82:83], v[62:63], v[82:83]
	v_fma_f64 v[84:85], v[62:63], v[80:81], -v[84:85]
	v_fmac_f64_e32 v[82:83], v[64:65], v[80:81]
	v_cvt_f32_f64_e32 v80, v[84:85]
	v_cvt_f32_f64_e32 v81, v[82:83]
	v_cvt_pk_bf16_f32 v3, v80, s0
	global_store_dwordx2 v[74:75], v[80:81], off
	v_cvt_pk_bf16_f32 v7, v81, s0
	global_store_short v[78:79], v3, off offset:1024
	global_store_short v[78:79], v7, off offset:3072
	v_lshlrev_b32_e32 v3, 16, v3
	v_lshlrev_b32_e32 v7, 16, v7
	v_sub_f32_e32 v3, v80, v3
	v_sub_f32_e32 v7, v81, v7
	v_cvt_pk_bf16_f32 v3, v3, s0
	v_cvt_pk_bf16_f32 v7, v7, s0
	global_store_short v[76:77], v3, off offset:1024
	global_store_short v[76:77], v7, off offset:3072
	v_lshl_add_u64 v[76:77], s[4:5], 0, v[66:67]
	v_add_co_u32_e32 v78, vcc, s56, v76
	v_lshl_add_u64 v[74:75], s[4:5], 0, v[72:73]
	s_nop 0
	v_addc_co_u32_e32 v79, vcc, 0, v77, vcc
	v_add_co_u32_e32 v76, vcc, s57, v76
	v_lshl_add_u64 v[66:67], v[66:67], 0, 2
	v_lshl_add_u64 v[72:73], v[72:73], 0, 8
	v_addc_co_u32_e32 v77, vcc, 0, v77, vcc
	v_cvt_f64_f32_e32 v[82:83], v103
	v_cvt_f64_f32_e32 v[80:81], v119
	v_mul_f64 v[84:85], v[64:65], v[82:83]
	v_mul_f64 v[82:83], v[62:63], v[82:83]
	v_fma_f64 v[84:85], v[62:63], v[80:81], -v[84:85]
	v_fmac_f64_e32 v[82:83], v[64:65], v[80:81]
	v_cvt_f32_f64_e32 v80, v[84:85]
	v_cvt_f32_f64_e32 v81, v[82:83]
	v_cvt_pk_bf16_f32 v3, v80, s0
	global_store_dwordx2 v[74:75], v[80:81], off
	v_cvt_pk_bf16_f32 v7, v81, s0
	global_store_short v[78:79], v3, off offset:1024
	global_store_short v[78:79], v7, off offset:3072
	v_lshlrev_b32_e32 v3, 16, v3
	v_lshlrev_b32_e32 v7, 16, v7
	v_sub_f32_e32 v3, v80, v3
	v_sub_f32_e32 v7, v81, v7
	v_cvt_pk_bf16_f32 v3, v3, s0
	v_cvt_pk_bf16_f32 v7, v7, s0
	global_store_short v[76:77], v3, off offset:1024
	global_store_short v[76:77], v7, off offset:3072
	v_lshl_add_u64 v[76:77], s[4:5], 0, v[66:67]
	v_add_co_u32_e32 v78, vcc, s56, v76
	v_lshl_add_u64 v[74:75], s[4:5], 0, v[72:73]
	s_nop 0
	v_addc_co_u32_e32 v79, vcc, 0, v77, vcc
	v_add_co_u32_e32 v76, vcc, s57, v76
	v_lshl_add_u64 v[66:67], v[66:67], 0, 2
	v_lshl_add_u64 v[72:73], v[72:73], 0, 8
	v_addc_co_u32_e32 v77, vcc, 0, v77, vcc
	v_cvt_f64_f32_e32 v[82:83], v104
	v_cvt_f64_f32_e32 v[80:81], v120
	v_mul_f64 v[84:85], v[64:65], v[82:83]
	v_mul_f64 v[82:83], v[62:63], v[82:83]
	v_fma_f64 v[84:85], v[62:63], v[80:81], -v[84:85]
	v_fmac_f64_e32 v[82:83], v[64:65], v[80:81]
	v_cvt_f32_f64_e32 v80, v[84:85]
	v_cvt_f32_f64_e32 v81, v[82:83]
; __device__ __forceinline__ bf16_t f2bf(float f) { return (bf16_t)(cvt_pk_bf16(f, 0.f) & 0xffffu); }
; __device__ __forceinline__ float bf2f(bf16_t b) { return __uint_as_float(((unsigned)b) << 16); }
; __device__ __forceinline__ void phase_prepass(ParamsK p, LAS unsigned char* lds) {
;     ...
;         for (int n = 0; n < 16; ++n) { const double b_r = br[n], b_i = bi[n]; const float vr = (float)(fr * b_r - fi * b_i), vi = (float)(fr * b_i + fi * b_r);
;             bo[n] = (f32x2){vr, vi}; const bf16_t hr = f2bf(vr), hi = f2bf(vi);
;             bmt[pp * 16 + n] = hr; bmt[(64 + pp) * 16 + n] = hi; bmt[2048 + pp * 16 + n] = f2bf(vr - bf2f(hr)); bmt[2048 + (64 + pp) * 16 + n] = f2bf(vi - bf2f(hi)); }
	v_cvt_pk_bf16_f32 v3, v80, s0
	global_store_dwordx2 v[74:75], v[80:81], off
	v_cvt_pk_bf16_f32 v7, v81, s0
	global_store_short v[78:79], v3, off offset:1024
	global_store_short v[78:79], v7, off offset:3072
	v_lshlrev_b32_e32 v3, 16, v3
	v_lshlrev_b32_e32 v7, 16, v7
	v_sub_f32_e32 v3, v80, v3
	v_sub_f32_e32 v7, v81, v7
	v_cvt_pk_bf16_f32 v3, v3, s0
	v_cvt_pk_bf16_f32 v7, v7, s0
	global_store_short v[76:77], v3, off offset:1024
	global_store_short v[76:77], v7, off offset:3072
	v_lshl_add_u64 v[76:77], s[4:5], 0, v[66:67]
	v_add_co_u32_e32 v78, vcc, s56, v76
	v_lshl_add_u64 v[74:75], s[4:5], 0, v[72:73]
	s_nop 0
	v_addc_co_u32_e32 v79, vcc, 0, v77, vcc
	v_add_co_u32_e32 v76, vcc, s57, v76
	v_lshl_add_u64 v[66:67], v[66:67], 0, 2
	v_lshl_add_u64 v[72:73], v[72:73], 0, 8
	v_addc_co_u32_e32 v77, vcc, 0, v77, vcc
	v_cvt_f64_f32_e32 v[82:83], v105
	v_cvt_f64_f32_e32 v[80:81], v121
	v_mul_f64 v[84:85], v[64:65], v[82:83]
	v_mul_f64 v[82:83], v[62:63], v[82:83]
	v_fma_f64 v[84:85], v[62:63], v[80:81], -v[84:85]
	v_fmac_f64_e32 v[82:83], v[64:65], v[80:81]
	v_cvt_f32_f64_e32 v80, v[84:85]
	v_cvt_f32_f64_e32 v81, v[82:83]
	v_cvt_pk_bf16_f32 v3, v80, s0
	global_store_dwordx2 v[74:75], v[80:81], off
	v_cvt_pk_bf16_f32 v7, v81, s0
	global_store_short v[78:79], v3, off offset:1024
	global_store_short v[78:79], v7, off offset:3072
	v_lshlrev_b32_e32 v3, 16, v3
	v_lshlrev_b32_e32 v7, 16, v7
	v_sub_f32_e32 v3, v80, v3
	v_sub_f32_e32 v7, v81, v7
	v_cvt_pk_bf16_f32 v3, v3, s0
	v_cvt_pk_bf16_f32 v7, v7, s0
	global_store_short v[76:77], v3, off offset:1024
	global_store_short v[76:77], v7, off offset:3072
	v_lshl_add_u64 v[76:77], s[4:5], 0, v[66:67]
	v_add_co_u32_e32 v78, vcc, s56, v76
	v_lshl_add_u64 v[74:75], s[4:5], 0, v[72:73]
	s_nop 0
	v_addc_co_u32_e32 v79, vcc, 0, v77, vcc
	v_add_co_u32_e32 v76, vcc, s57, v76
	v_lshl_add_u64 v[66:67], v[66:67], 0, 2
	v_lshl_add_u64 v[72:73], v[72:73], 0, 8
	v_addc_co_u32_e32 v77, vcc, 0, v77, vcc
	v_cvt_f64_f32_e32 v[82:83], v106
	v_cvt_f64_f32_e32 v[80:81], v122
	v_mul_f64 v[84:85], v[64:65], v[82:83]
	v_mul_f64 v[82:83], v[62:63], v[82:83]
	v_fma_f64 v[84:85], v[62:63], v[80:81], -v[84:85]
	v_fmac_f64_e32 v[82:83], v[64:65], v[80:81]
	v_cvt_f32_f64_e32 v80, v[84:85]
	v_cvt_f32_f64_e32 v81, v[82:83]
	v_cvt_pk_bf16_f32 v3, v80, s0
	global_store_dwordx2 v[74:75], v[80:81], off
	v_cvt_pk_bf16_f32 v7, v81, s0
	global_store_short v[78:79], v3, off offset:1024
	global_store_short v[78:79], v7, off offset:3072
	v_lshlrev_b32_e32 v3, 16, v3
	v_lshlrev_b32_e32 v7, 16, v7
	v_sub_f32_e32 v3, v80, v3
	v_sub_f32_e32 v7, v81, v7
	v_cvt_pk_bf16_f32 v3, v3, s0
	v_cvt_pk_bf16_f32 v7, v7, s0
	global_store_short v[76:77], v3, off offset:1024
	global_store_short v[76:77], v7, off offset:3072
	v_lshl_add_u64 v[76:77], s[4:5], 0, v[66:67]
	v_add_co_u32_e32 v78, vcc, s56, v76
	v_lshl_add_u64 v[74:75], s[4:5], 0, v[72:73]
	s_nop 0
	v_addc_co_u32_e32 v79, vcc, 0, v77, vcc
	v_add_co_u32_e32 v76, vcc, s57, v76
	v_lshl_add_u64 v[66:67], v[66:67], 0, 2
	v_lshl_add_u64 v[72:73], v[72:73], 0, 8
	v_addc_co_u32_e32 v77, vcc, 0, v77, vcc
	v_cvt_f64_f32_e32 v[82:83], v107
	v_cvt_f64_f32_e32 v[80:81], v123
	v_mul_f64 v[84:85], v[64:65], v[82:83]
	v_mul_f64 v[82:83], v[62:63], v[82:83]
	v_fma_f64 v[84:85], v[62:63], v[80:81], -v[84:85]
	v_fmac_f64_e32 v[82:83], v[64:65], v[80:81]
	v_cvt_f32_f64_e32 v80, v[84:85]
	v_cvt_f32_f64_e32 v81, v[82:83]
	v_cvt_pk_bf16_f32 v3, v80, s0
	global_store_dwordx2 v[74:75], v[80:81], off
	v_cvt_pk_bf16_f32 v7, v81, s0
	global_store_short v[78:79], v3, off offset:1024
	global_store_short v[78:79], v7, off offset:3072
	v_lshlrev_b32_e32 v3, 16, v3
	v_lshlrev_b32_e32 v7, 16, v7
	v_sub_f32_e32 v3, v80, v3
	v_sub_f32_e32 v7, v81, v7
	v_cvt_pk_bf16_f32 v3, v3, s0
	v_cvt_pk_bf16_f32 v7, v7, s0
	global_store_short v[76:77], v3, off offset:1024
	global_store_short v[76:77], v7, off offset:3072
	v_lshl_add_u64 v[76:77], s[4:5], 0, v[66:67]
	v_add_co_u32_e32 v78, vcc, s56, v76
	v_lshl_add_u64 v[74:75], s[4:5], 0, v[72:73]
	s_nop 0
	v_addc_co_u32_e32 v79, vcc, 0, v77, vcc
	v_add_co_u32_e32 v76, vcc, s57, v76
	v_lshl_add_u64 v[66:67], v[66:67], 0, 2
	v_lshl_add_u64 v[72:73], v[72:73], 0, 8
	v_addc_co_u32_e32 v77, vcc, 0, v77, vcc
	v_cvt_f64_f32_e32 v[82:83], v108
	v_cvt_f64_f32_e32 v[80:81], v124
	v_mul_f64 v[84:85], v[64:65], v[82:83]
	v_mul_f64 v[82:83], v[62:63], v[82:83]
	v_fma_f64 v[84:85], v[62:63], v[80:81], -v[84:85]
	v_fmac_f64_e32 v[82:83], v[64:65], v[80:81]
	v_cvt_f32_f64_e32 v80, v[84:85]
	v_cvt_f32_f64_e32 v81, v[82:83]
	v_cvt_pk_bf16_f32 v3, v80, s0
	global_store_dwordx2 v[74:75], v[80:81], off
	v_cvt_pk_bf16_f32 v7, v81, s0
	global_store_short v[78:79], v3, off offset:1024
	global_store_short v[78:79], v7, off offset:3072
	v_lshlrev_b32_e32 v3, 16, v3
	v_lshlrev_b32_e32 v7, 16, v7
	v_sub_f32_e32 v3, v80, v3
	v_sub_f32_e32 v7, v81, v7
	v_cvt_pk_bf16_f32 v3, v3, s0
	v_cvt_pk_bf16_f32 v7, v7, s0
	global_store_short v[76:77], v3, off offset:1024
	global_store_short v[76:77], v7, off offset:3072
	v_lshl_add_u64 v[76:77], s[4:5], 0, v[66:67]
	v_add_co_u32_e32 v78, vcc, s56, v76
	v_lshl_add_u64 v[74:75], s[4:5], 0, v[72:73]
	s_nop 0
	v_addc_co_u32_e32 v79, vcc, 0, v77, vcc
	v_add_co_u32_e32 v76, vcc, s57, v76
	v_lshl_add_u64 v[66:67], v[66:67], 0, 2
	v_lshl_add_u64 v[72:73], v[72:73], 0, 8
	v_addc_co_u32_e32 v77, vcc, 0, v77, vcc
	v_cvt_f64_f32_e32 v[82:83], v109
	v_cvt_f64_f32_e32 v[80:81], v125
	v_mul_f64 v[84:85], v[64:65], v[82:83]
	v_mul_f64 v[82:83], v[62:63], v[82:83]
	v_fma_f64 v[84:85], v[62:63], v[80:81], -v[84:85]
	v_fmac_f64_e32 v[82:83], v[64:65], v[80:81]
	v_cvt_f32_f64_e32 v80, v[84:85]
	v_cvt_f32_f64_e32 v81, v[82:83]
; __device__ __forceinline__ bf16_t f2bf(float f) { return (bf16_t)(cvt_pk_bf16(f, 0.f) & 0xffffu); }
; __device__ __forceinline__ float bf2f(bf16_t b) { return __uint_as_float(((unsigned)b) << 16); }
; __device__ __forceinline__ void phase_prepass(ParamsK p, LAS unsigned char* lds) {
;     ...
;         for (int n = 0; n < 16; ++n) { const double b_r = br[n], b_i = bi[n]; const float vr = (float)(fr * b_r - fi * b_i), vi = (float)(fr * b_i + fi * b_r);
;             bo[n] = (f32x2){vr, vi}; const bf16_t hr = f2bf(vr), hi = f2bf(vi);
;             bmt[pp * 16 + n] = hr; bmt[(64 + pp) * 16 + n] = hi; bmt[2048 + pp * 16 + n] = f2bf(vr - bf2f(hr)); bmt[2048 + (64 + pp) * 16 + n] = f2bf(vi - bf2f(hi)); }
	v_cvt_pk_bf16_f32 v3, v80, s0
	global_store_dwordx2 v[74:75], v[80:81], off
	v_cvt_pk_bf16_f32 v7, v81, s0
	global_store_short v[78:79], v3, off offset:1024
	global_store_short v[78:79], v7, off offset:3072
	v_lshlrev_b32_e32 v3, 16, v3
	v_lshlrev_b32_e32 v7, 16, v7
	v_sub_f32_e32 v3, v80, v3
	v_sub_f32_e32 v7, v81, v7
	v_cvt_pk_bf16_f32 v3, v3, s0
	v_cvt_pk_bf16_f32 v7, v7, s0
	global_store_short v[76:77], v3, off offset:1024
	global_store_short v[76:77], v7, off offset:3072
	v_lshl_add_u64 v[76:77], s[4:5], 0, v[66:67]
	v_add_co_u32_e32 v78, vcc, s56, v76
	v_lshl_add_u64 v[74:75], s[4:5], 0, v[72:73]
	s_nop 0
	v_addc_co_u32_e32 v79, vcc, 0, v77, vcc
	v_add_co_u32_e32 v76, vcc, s57, v76
	v_lshl_add_u64 v[66:67], v[66:67], 0, 2
	v_lshl_add_u64 v[72:73], v[72:73], 0, 8
	v_addc_co_u32_e32 v77, vcc, 0, v77, vcc
	v_cvt_f64_f32_e32 v[82:83], v110
	v_cvt_f64_f32_e32 v[80:81], v126
	v_mul_f64 v[84:85], v[64:65], v[82:83]
	v_mul_f64 v[82:83], v[62:63], v[82:83]
	v_fma_f64 v[84:85], v[62:63], v[80:81], -v[84:85]
	v_fmac_f64_e32 v[82:83], v[64:65], v[80:81]
	v_cvt_f32_f64_e32 v80, v[84:85]
	v_cvt_f32_f64_e32 v81, v[82:83]
	v_cvt_pk_bf16_f32 v3, v80, s0
	global_store_dwordx2 v[74:75], v[80:81], off
	v_cvt_pk_bf16_f32 v7, v81, s0
	global_store_short v[78:79], v3, off offset:1024
	global_store_short v[78:79], v7, off offset:3072
	v_lshlrev_b32_e32 v3, 16, v3
	v_lshlrev_b32_e32 v7, 16, v7
	v_sub_f32_e32 v3, v80, v3
	v_sub_f32_e32 v7, v81, v7
	v_cvt_pk_bf16_f32 v3, v3, s0
	v_cvt_pk_bf16_f32 v7, v7, s0
	global_store_short v[76:77], v3, off offset:1024
	global_store_short v[76:77], v7, off offset:3072
	v_lshl_add_u64 v[76:77], s[4:5], 0, v[66:67]
	v_add_co_u32_e32 v78, vcc, s56, v76
	v_lshl_add_u64 v[74:75], s[4:5], 0, v[72:73]
	s_nop 0
	v_addc_co_u32_e32 v79, vcc, 0, v77, vcc
	v_add_co_u32_e32 v76, vcc, s57, v76
	v_lshl_add_u64 v[66:67], v[66:67], 0, 2
	v_lshl_add_u64 v[72:73], v[72:73], 0, 8
	v_addc_co_u32_e32 v77, vcc, 0, v77, vcc
	v_cvt_f64_f32_e32 v[82:83], v111
	v_cvt_f64_f32_e32 v[80:81], v127
	v_mul_f64 v[84:85], v[64:65], v[82:83]
	v_mul_f64 v[82:83], v[62:63], v[82:83]
	v_fma_f64 v[84:85], v[62:63], v[80:81], -v[84:85]
	v_fmac_f64_e32 v[82:83], v[64:65], v[80:81]
	v_cvt_f32_f64_e32 v80, v[84:85]
	v_cvt_f32_f64_e32 v81, v[82:83]
	v_cvt_pk_bf16_f32 v3, v80, s0
	global_store_dwordx2 v[74:75], v[80:81], off
	v_cvt_pk_bf16_f32 v7, v81, s0
	global_store_short v[78:79], v3, off offset:1024
	global_store_short v[78:79], v7, off offset:3072
	v_lshlrev_b32_e32 v3, 16, v3
	v_lshlrev_b32_e32 v7, 16, v7
	v_sub_f32_e32 v3, v80, v3
	v_sub_f32_e32 v7, v81, v7
	v_cvt_pk_bf16_f32 v3, v3, s0
	v_cvt_pk_bf16_f32 v7, v7, s0
	global_store_short v[76:77], v3, off offset:1024
	global_store_short v[76:77], v7, off offset:3072
	v_lshl_add_u64 v[76:77], s[4:5], 0, v[66:67]
	v_add_co_u32_e32 v78, vcc, s56, v76
	v_lshl_add_u64 v[74:75], s[4:5], 0, v[72:73]
	s_nop 0
	v_addc_co_u32_e32 v79, vcc, 0, v77, vcc
	v_add_co_u32_e32 v76, vcc, s57, v76
	v_lshl_add_u64 v[66:67], v[66:67], 0, 2
	v_lshl_add_u64 v[72:73], v[72:73], 0, 8
	v_addc_co_u32_e32 v77, vcc, 0, v77, vcc
	v_cvt_f64_f32_e32 v[82:83], v112
	v_cvt_f64_f32_e32 v[80:81], v128
	v_mul_f64 v[84:85], v[64:65], v[82:83]
	v_mul_f64 v[82:83], v[62:63], v[82:83]
	v_fma_f64 v[84:85], v[62:63], v[80:81], -v[84:85]
	v_fmac_f64_e32 v[82:83], v[64:65], v[80:81]
	v_cvt_f32_f64_e32 v80, v[84:85]
	v_cvt_f32_f64_e32 v81, v[82:83]
	v_cvt_pk_bf16_f32 v3, v80, s0
	global_store_dwordx2 v[74:75], v[80:81], off
	v_cvt_pk_bf16_f32 v7, v81, s0
	global_store_short v[78:79], v3, off offset:1024
	global_store_short v[78:79], v7, off offset:3072
	v_lshlrev_b32_e32 v3, 16, v3
	v_lshlrev_b32_e32 v7, 16, v7
	v_sub_f32_e32 v3, v80, v3
	v_sub_f32_e32 v7, v81, v7
	v_cvt_pk_bf16_f32 v3, v3, s0
	v_cvt_pk_bf16_f32 v7, v7, s0
	global_store_short v[76:77], v3, off offset:1024
	global_store_short v[76:77], v7, off offset:3072
	v_lshl_add_u64 v[76:77], s[4:5], 0, v[66:67]
	v_add_co_u32_e32 v78, vcc, s56, v76
	v_lshl_add_u64 v[74:75], s[4:5], 0, v[72:73]
	s_nop 0
	v_addc_co_u32_e32 v79, vcc, 0, v77, vcc
	v_add_co_u32_e32 v76, vcc, s57, v76
	v_lshl_add_u64 v[66:67], v[66:67], 0, 2
	v_lshl_add_u64 v[72:73], v[72:73], 0, 8
	v_addc_co_u32_e32 v77, vcc, 0, v77, vcc
	v_cvt_f64_f32_e32 v[82:83], v113
	v_cvt_f64_f32_e32 v[80:81], v129
	v_mul_f64 v[84:85], v[64:65], v[82:83]
	v_mul_f64 v[82:83], v[62:63], v[82:83]
	v_fma_f64 v[84:85], v[62:63], v[80:81], -v[84:85]
	v_fmac_f64_e32 v[82:83], v[64:65], v[80:81]
	v_cvt_f32_f64_e32 v80, v[84:85]
	v_cvt_f32_f64_e32 v81, v[82:83]
	v_cvt_pk_bf16_f32 v3, v80, s0
	global_store_dwordx2 v[74:75], v[80:81], off
	v_cvt_pk_bf16_f32 v7, v81, s0
	global_store_short v[78:79], v3, off offset:1024
	global_store_short v[78:79], v7, off offset:3072
	v_lshlrev_b32_e32 v3, 16, v3
	v_lshlrev_b32_e32 v7, 16, v7
	v_sub_f32_e32 v3, v80, v3
	v_sub_f32_e32 v7, v81, v7
	v_cvt_pk_bf16_f32 v3, v3, s0
	v_cvt_pk_bf16_f32 v7, v7, s0
	global_store_short v[76:77], v3, off offset:1024
	global_store_short v[76:77], v7, off offset:3072
	v_lshl_add_u64 v[76:77], s[4:5], 0, v[66:67]
	v_add_co_u32_e32 v78, vcc, s56, v76
	v_lshl_add_u64 v[74:75], s[4:5], 0, v[72:73]
	s_nop 0
	v_addc_co_u32_e32 v79, vcc, 0, v77, vcc
	v_add_co_u32_e32 v76, vcc, s57, v76
	v_lshl_add_u64 v[66:67], v[66:67], 0, 2
	v_lshl_add_u64 v[72:73], v[72:73], 0, 8
	v_addc_co_u32_e32 v77, vcc, 0, v77, vcc
	v_cvt_f64_f32_e32 v[82:83], v114
	v_cvt_f64_f32_e32 v[80:81], v130
	v_mul_f64 v[84:85], v[64:65], v[82:83]
	v_mul_f64 v[82:83], v[62:63], v[82:83]
	v_fma_f64 v[84:85], v[62:63], v[80:81], -v[84:85]
	v_fmac_f64_e32 v[82:83], v[64:65], v[80:81]
	v_cvt_f32_f64_e32 v80, v[84:85]
	v_cvt_f32_f64_e32 v81, v[82:83]
; __device__ __forceinline__ bf16_t f2bf(float f) { return (bf16_t)(cvt_pk_bf16(f, 0.f) & 0xffffu); }
; __device__ __forceinline__ float bf2f(bf16_t b) { return __uint_as_float(((unsigned)b) << 16); }
; __device__ __forceinline__ void phase_prepass(ParamsK p, LAS unsigned char* lds) {
;     ...
;         for (int n = 0; n < 16; ++n) { const double b_r = br[n], b_i = bi[n]; const float vr = (float)(fr * b_r - fi * b_i), vi = (float)(fr * b_i + fi * b_r);
;             bo[n] = (f32x2){vr, vi}; const bf16_t hr = f2bf(vr), hi = f2bf(vi);
;             bmt[pp * 16 + n] = hr; bmt[(64 + pp) * 16 + n] = hi; bmt[2048 + pp * 16 + n] = f2bf(vr - bf2f(hr)); bmt[2048 + (64 + pp) * 16 + n] = f2bf(vi - bf2f(hi)); }
;         bf16_t* cm = (bf16_t*)(p->ws + WS_S5C) + (size_t)(l * 64 + g) * 16 * 128;
;         const float* cr = p->in[13] + (size_t)(l * 64 + g) * 16 * 64; const float* ci = p->in[14] + (size_t)(l * 64 + g) * 16 * 64;
; #pragma unroll 1
;         for (int n = 0; n < 16; ++n) { cm[n * 128 + pp] = f2bf(cr[n * 64 + pp]); cm[n * 128 + 64 + pp] = f2bf(-ci[n * 64 + pp]); }
	v_cvt_pk_bf16_f32 v3, v80, s0
	global_store_dwordx2 v[74:75], v[80:81], off
	v_cvt_pk_bf16_f32 v7, v81, s0
	global_store_short v[78:79], v3, off offset:1024
	global_store_short v[78:79], v7, off offset:3072
	v_lshlrev_b32_e32 v3, 16, v3
	v_lshlrev_b32_e32 v7, 16, v7
	v_sub_f32_e32 v3, v80, v3
	v_sub_f32_e32 v7, v81, v7
	v_cvt_pk_bf16_f32 v3, v3, s0
	v_cvt_pk_bf16_f32 v7, v7, s0
	global_store_short v[76:77], v3, off offset:1024
	global_store_short v[76:77], v7, off offset:3072
	v_lshl_add_u64 v[76:77], s[4:5], 0, v[66:67]
	v_add_co_u32_e32 v78, vcc, s56, v76
	v_lshl_add_u64 v[74:75], s[4:5], 0, v[72:73]
	s_nop 0
	v_addc_co_u32_e32 v79, vcc, 0, v77, vcc
	v_add_co_u32_e32 v76, vcc, s57, v76
	v_lshl_add_u64 v[66:67], v[66:67], 0, 2
	v_lshl_add_u64 v[72:73], v[72:73], 0, 8
	v_addc_co_u32_e32 v77, vcc, 0, v77, vcc
	v_cvt_f64_f32_e32 v[82:83], v115
	v_cvt_f64_f32_e32 v[80:81], v131
	v_mul_f64 v[84:85], v[64:65], v[82:83]
	v_mul_f64 v[82:83], v[62:63], v[82:83]
	v_fma_f64 v[84:85], v[62:63], v[80:81], -v[84:85]
	v_fmac_f64_e32 v[82:83], v[64:65], v[80:81]
	v_cvt_f32_f64_e32 v80, v[84:85]
	v_cvt_f32_f64_e32 v81, v[82:83]
	v_cvt_pk_bf16_f32 v3, v80, s0
	global_store_dwordx2 v[74:75], v[80:81], off
	v_cvt_pk_bf16_f32 v7, v81, s0
	global_store_short v[78:79], v3, off offset:1024
	global_store_short v[78:79], v7, off offset:3072
	v_lshlrev_b32_e32 v3, 16, v3
	v_lshlrev_b32_e32 v7, 16, v7
	v_sub_f32_e32 v3, v80, v3
	v_sub_f32_e32 v7, v81, v7
	v_cvt_pk_bf16_f32 v3, v3, s0
	v_cvt_pk_bf16_f32 v7, v7, s0
	global_store_short v[76:77], v3, off offset:1024
	global_store_short v[76:77], v7, off offset:3072
	s_load_dwordx4 s[60:63], s[12:13], 0x68
	v_lshlrev_b64 v[64:65], 12, v[60:61]
	v_lshl_add_u64 v[60:61], s[4:5], 0, v[64:65]
	v_lshl_add_u64 v[60:61], v[60:61], 0, s[52:53]
	s_mov_b32 s54, 1
	s_waitcnt lgkmcnt(0)
	v_lshl_add_u64 v[62:63], s[60:61], 0, v[64:65]
	v_lshl_add_u64 v[64:65], s[62:63], 0, v[64:65]
	s_mov_b32 s55, 0
	s_mov_b32 s59, 16
.LBB0_137:
	v_or_b32_e32 v8, 0, v4
	v_mov_b32_e32 v67, v9
	v_or_b32_e32 v66, 64, v1
	v_lshlrev_b64 v[68:69], 2, v[8:9]
	v_lshlrev_b64 v[66:67], 2, v[66:67]
	v_lshl_add_u64 v[70:71], v[62:63], 0, v[68:69]
	v_lshl_add_u64 v[68:69], v[64:65], 0, v[68:69]
	v_lshl_add_u64 v[72:73], v[62:63], 0, v[66:67]
	v_lshl_add_u64 v[66:67], v[64:65], 0, v[66:67]
	global_load_dword v100, v[68:69], off
	global_load_dword v101, v[66:67], off
	global_load_dword v102, v[70:71], off
	global_load_dword v103, v[72:73], off
	v_or_b32_e32 v8, 0x80, v4
	v_mov_b32_e32 v67, v9
	v_or_b32_e32 v66, 0xc0, v1
	v_lshlrev_b64 v[68:69], 2, v[8:9]
	v_lshlrev_b64 v[66:67], 2, v[66:67]
	v_lshl_add_u64 v[70:71], v[62:63], 0, v[68:69]
	v_lshl_add_u64 v[68:69], v[64:65], 0, v[68:69]
	v_lshl_add_u64 v[72:73], v[62:63], 0, v[66:67]
	v_lshl_add_u64 v[66:67], v[64:65], 0, v[66:67]
	global_load_dword v104, v[68:69], off
	global_load_dword v105, v[66:67], off
	global_load_dword v106, v[70:71], off
	global_load_dword v107, v[72:73], off
	v_or_b32_e32 v8, 0x100, v4
	v_mov_b32_e32 v67, v9
	v_or_b32_e32 v66, 0x140, v1
	v_lshlrev_b64 v[68:69], 2, v[8:9]
	v_lshlrev_b64 v[66:67], 2, v[66:67]
	v_lshl_add_u64 v[70:71], v[62:63], 0, v[68:69]
	v_lshl_add_u64 v[68:69], v[64:65], 0, v[68:69]
	v_lshl_add_u64 v[72:73], v[62:63], 0, v[66:67]
	v_lshl_add_u64 v[66:67], v[64:65], 0, v[66:67]
	global_load_dword v108, v[68:69], off
	global_load_dword v109, v[66:67], off
	global_load_dword v110, v[70:71], off
	global_load_dword v111, v[72:73], off
	v_or_b32_e32 v8, 0x180, v4
	v_mov_b32_e32 v67, v9
	v_or_b32_e32 v66, 0x1c0, v1
	v_lshlrev_b64 v[68:69], 2, v[8:9]
	v_lshlrev_b64 v[66:67], 2, v[66:67]
	v_lshl_add_u64 v[70:71], v[62:63], 0, v[68:69]
	v_lshl_add_u64 v[68:69], v[64:65], 0, v[68:69]
	v_lshl_add_u64 v[72:73], v[62:63], 0, v[66:67]
	v_lshl_add_u64 v[66:67], v[64:65], 0, v[66:67]
	global_load_dword v112, v[68:69], off
	global_load_dword v113, v[66:67], off
	global_load_dword v114, v[70:71], off
	global_load_dword v115, v[72:73], off
	v_or_b32_e32 v8, 0x200, v4
	v_mov_b32_e32 v67, v9
	v_or_b32_e32 v66, 0x240, v1
	v_lshlrev_b64 v[68:69], 2, v[8:9]
	v_lshlrev_b64 v[66:67], 2, v[66:67]
	v_lshl_add_u64 v[70:71], v[62:63], 0, v[68:69]
	v_lshl_add_u64 v[68:69], v[64:65], 0, v[68:69]
	v_lshl_add_u64 v[72:73], v[62:63], 0, v[66:67]
	v_lshl_add_u64 v[66:67], v[64:65], 0, v[66:67]
	global_load_dword v116, v[68:69], off
	global_load_dword v117, v[66:67], off
	global_load_dword v118, v[70:71], off
	global_load_dword v119, v[72:73], off
	v_or_b32_e32 v8, 0x280, v4
	v_mov_b32_e32 v67, v9
	v_or_b32_e32 v66, 0x2c0, v1
	v_lshlrev_b64 v[68:69], 2, v[8:9]
	v_lshlrev_b64 v[66:67], 2, v[66:67]
	v_lshl_add_u64 v[70:71], v[62:63], 0, v[68:69]
	v_lshl_add_u64 v[68:69], v[64:65], 0, v[68:69]
	v_lshl_add_u64 v[72:73], v[62:63], 0, v[66:67]
	v_lshl_add_u64 v[66:67], v[64:65], 0, v[66:67]
	global_load_dword v120, v[68:69], off
	global_load_dword v121, v[66:67], off
	global_load_dword v122, v[70:71], off
	global_load_dword v123, v[72:73], off
	v_or_b32_e32 v8, 0x300, v4
	v_mov_b32_e32 v67, v9
	v_or_b32_e32 v66, 0x340, v1
	v_lshlrev_b64 v[68:69], 2, v[8:9]
	v_lshlrev_b64 v[66:67], 2, v[66:67]
	v_lshl_add_u64 v[70:71], v[62:63], 0, v[68:69]
	v_lshl_add_u64 v[68:69], v[64:65], 0, v[68:69]
	v_lshl_add_u64 v[72:73], v[62:63], 0, v[66:67]
	v_lshl_add_u64 v[66:67], v[64:65], 0, v[66:67]
	global_load_dword v124, v[68:69], off
	global_load_dword v125, v[66:67], off
	global_load_dword v126, v[70:71], off
	global_load_dword v127, v[72:73], off
	v_or_b32_e32 v8, 0x380, v4
	v_mov_b32_e32 v67, v9
	v_or_b32_e32 v66, 0x3c0, v1
	v_lshlrev_b64 v[68:69], 2, v[8:9]
	v_lshlrev_b64 v[66:67], 2, v[66:67]
	v_lshl_add_u64 v[70:71], v[62:63], 0, v[68:69]
	v_lshl_add_u64 v[68:69], v[64:65], 0, v[68:69]
	v_lshl_add_u64 v[72:73], v[62:63], 0, v[66:67]
	v_lshl_add_u64 v[66:67], v[64:65], 0, v[66:67]
	global_load_dword v128, v[68:69], off
	global_load_dword v129, v[66:67], off
	global_load_dword v130, v[70:71], off
	global_load_dword v131, v[72:73], off
	s_waitcnt vmcnt(0)
; __device__ __forceinline__ bf16_t f2bf(float f) { return (bf16_t)(cvt_pk_bf16(f, 0.f) & 0xffffu); }
; __device__ __forceinline__ void phase_prepass(ParamsK p, LAS unsigned char* lds) {
;     ...
;         bf16_t* cm = (bf16_t*)(p->ws + WS_S5C) + (size_t)(l * 64 + g) * 16 * 128;
;         const float* cr = p->in[13] + (size_t)(l * 64 + g) * 16 * 64; const float* ci = p->in[14] + (size_t)(l * 64 + g) * 16 * 64;
; #pragma unroll 1
;         for (int n = 0; n < 16; ++n) { cm[n * 128 + pp] = f2bf(cr[n * 64 + pp]); cm[n * 128 + 64 + pp] = f2bf(-ci[n * 64 + pp]); }
;     }
	v_or_b32_e32 v8, 0, v4
	v_mov_b32_e32 v67, v9
	v_or_b32_e32 v66, 0x80, v1
	v_lshl_add_u64 v[70:71], v[8:9], 1, v[60:61]
	v_lshl_add_u64 v[66:67], v[66:67], 1, v[60:61]
	v_pk_add_f32 v[68:69], v[100:101], 0 neg_lo:[1,1] neg_hi:[1,1]
	v_cvt_pk_bf16_f32 v3, v102, v103
	global_store_short v[70:71], v3, off
	global_store_short_d16_hi v[66:67], v3, off
	v_cvt_pk_bf16_f32 v3, v68, v69
	global_store_short v[70:71], v3, off offset:128
	global_store_short_d16_hi v[66:67], v3, off offset:128
	v_or_b32_e32 v8, 0x100, v4
	v_mov_b32_e32 v67, v9
	v_or_b32_e32 v66, 0x180, v1
	v_lshl_add_u64 v[70:71], v[8:9], 1, v[60:61]
	v_lshl_add_u64 v[66:67], v[66:67], 1, v[60:61]
	v_pk_add_f32 v[68:69], v[104:105], 0 neg_lo:[1,1] neg_hi:[1,1]
	v_cvt_pk_bf16_f32 v3, v106, v107
	global_store_short v[70:71], v3, off
	global_store_short_d16_hi v[66:67], v3, off
	v_cvt_pk_bf16_f32 v3, v68, v69
	global_store_short v[70:71], v3, off offset:128
	global_store_short_d16_hi v[66:67], v3, off offset:128
	v_or_b32_e32 v8, 0x200, v4
	v_mov_b32_e32 v67, v9
	v_or_b32_e32 v66, 0x280, v1
	v_lshl_add_u64 v[70:71], v[8:9], 1, v[60:61]
	v_lshl_add_u64 v[66:67], v[66:67], 1, v[60:61]
	v_pk_add_f32 v[68:69], v[108:109], 0 neg_lo:[1,1] neg_hi:[1,1]
	v_cvt_pk_bf16_f32 v3, v110, v111
	global_store_short v[70:71], v3, off
	global_store_short_d16_hi v[66:67], v3, off
	v_cvt_pk_bf16_f32 v3, v68, v69
	global_store_short v[70:71], v3, off offset:128
	global_store_short_d16_hi v[66:67], v3, off offset:128
	v_or_b32_e32 v8, 0x300, v4
	v_mov_b32_e32 v67, v9
	v_or_b32_e32 v66, 0x380, v1
	v_lshl_add_u64 v[70:71], v[8:9], 1, v[60:61]
	v_lshl_add_u64 v[66:67], v[66:67], 1, v[60:61]
	v_pk_add_f32 v[68:69], v[112:113], 0 neg_lo:[1,1] neg_hi:[1,1]
	v_cvt_pk_bf16_f32 v3, v114, v115
	global_store_short v[70:71], v3, off
	global_store_short_d16_hi v[66:67], v3, off
	v_cvt_pk_bf16_f32 v3, v68, v69
	global_store_short v[70:71], v3, off offset:128
	global_store_short_d16_hi v[66:67], v3, off offset:128
	v_or_b32_e32 v8, 0x400, v4
	v_mov_b32_e32 v67, v9
	v_or_b32_e32 v66, 0x480, v1
	v_lshl_add_u64 v[70:71], v[8:9], 1, v[60:61]
	v_lshl_add_u64 v[66:67], v[66:67], 1, v[60:61]
	v_pk_add_f32 v[68:69], v[116:117], 0 neg_lo:[1,1] neg_hi:[1,1]
	v_cvt_pk_bf16_f32 v3, v118, v119
	global_store_short v[70:71], v3, off
	global_store_short_d16_hi v[66:67], v3, off
	v_cvt_pk_bf16_f32 v3, v68, v69
	global_store_short v[70:71], v3, off offset:128
	global_store_short_d16_hi v[66:67], v3, off offset:128
	v_or_b32_e32 v8, 0x500, v4
	v_mov_b32_e32 v67, v9
	v_or_b32_e32 v66, 0x580, v1
	v_lshl_add_u64 v[70:71], v[8:9], 1, v[60:61]
	v_lshl_add_u64 v[66:67], v[66:67], 1, v[60:61]
	v_pk_add_f32 v[68:69], v[120:121], 0 neg_lo:[1,1] neg_hi:[1,1]
	v_cvt_pk_bf16_f32 v3, v122, v123
	global_store_short v[70:71], v3, off
	global_store_short_d16_hi v[66:67], v3, off
	v_cvt_pk_bf16_f32 v3, v68, v69
	global_store_short v[70:71], v3, off offset:128
	global_store_short_d16_hi v[66:67], v3, off offset:128
	v_or_b32_e32 v8, 0x600, v4
	v_mov_b32_e32 v67, v9
	v_or_b32_e32 v66, 0x680, v1
	v_lshl_add_u64 v[70:71], v[8:9], 1, v[60:61]
	v_lshl_add_u64 v[66:67], v[66:67], 1, v[60:61]
	v_pk_add_f32 v[68:69], v[124:125], 0 neg_lo:[1,1] neg_hi:[1,1]
	v_cvt_pk_bf16_f32 v3, v126, v127
	global_store_short v[70:71], v3, off
	global_store_short_d16_hi v[66:67], v3, off
	v_cvt_pk_bf16_f32 v3, v68, v69
	global_store_short v[70:71], v3, off offset:128
	global_store_short_d16_hi v[66:67], v3, off offset:128
	v_or_b32_e32 v8, 0x700, v4
	v_mov_b32_e32 v67, v9
	v_or_b32_e32 v66, 0x780, v1
	v_lshl_add_u64 v[70:71], v[8:9], 1, v[60:61]
	v_lshl_add_u64 v[66:67], v[66:67], 1, v[60:61]
	v_pk_add_f32 v[68:69], v[128:129], 0 neg_lo:[1,1] neg_hi:[1,1]
	v_cvt_pk_bf16_f32 v3, v130, v131
	global_store_short v[70:71], v3, off
	global_store_short_d16_hi v[66:67], v3, off
	v_cvt_pk_bf16_f32 v3, v68, v69
	global_store_short v[70:71], v3, off offset:128
	global_store_short_d16_hi v[66:67], v3, off offset:128
	v_add_u32_e32 v2, s6, v2
	v_cmp_lt_i32_e32 vcc, s58, v2
	v_lshl_add_u64 v[10:11], v[10:11], 0, s[18:19]
	v_lshl_add_u64 v[12:13], v[12:13], 0, s[22:23]
	s_or_b64 s[20:21], vcc, s[20:21]
	v_mov_b64_e32 v[60:61], s[4:5]
	s_andn2_b64 exec, exec, s[20:21]
	s_cbranch_execnz .LBB0_124
	s_or_b64 exec, exec, s[20:21]
